# EpiResid epilogues: non-temporal hint on the residual loads only (read-once stream)
# baseline (speedup 1.0000x reference)
;     __device__ __forceinline__ void operator()(Acc& acc, const Unit& u, int wr, int wc, int fr, int fq) const {
;         const size_t p0 = u.ooff + (size_t)(wr * 64 + fr) * D + wc * 32 + 8 * fq;
; #pragma unroll
;         for (int ai = 0; ai < 2; ++ai)
; #pragma unroll
;             for (int m = 0; m < 4; ++m)
; #pragma unroll
;                 for (int bj = 0; bj < 2; ++bj) {
;                     const size_t p = p0 + (size_t)(ai * 128 + m * 16) * D + bj * 128;
;                     const f32x4 r0 = *(const f32x4*)(R + p), r1 = *(const f32x4*)(R + p + 4);
;                     *(f32x4*)(O + p) = r0 + acc[ai][bj][m][0] * scale; *(f32x4*)(O + p + 4) = r1 + acc[ai][bj][m][1] * scale;
;                 }
.LBB0_202:
	v_lshl_add_u64 v[146:147], v[136:137], 0, s[80:81]
	v_readlane_b32 s16, v245, 3
	v_lshlrev_b64 v[146:147], 2, v[146:147]
	v_readlane_b32 s17, v245, 4
	v_readlane_b32 s18, v245, 5
	v_readlane_b32 s19, v245, 6
	v_lshl_add_u64 v[148:149], s[16:17], 0, v[146:147]
	global_load_dwordx4 v[154:157], v[148:149], off nt
	global_load_dwordx4 v[158:161], v[148:149], off offset:16 nt
	v_readlane_b32 s20, v245, 7
	v_readlane_b32 s21, v245, 8
	v_readlane_b32 s22, v245, 9
	v_readlane_b32 s23, v245, 10
	v_readlane_b32 s16, v244, 28
	v_readlane_b32 s18, v244, 30
	v_readlane_b32 s19, v244, 31
	s_mov_b64 s[0:1], 0x100000
	v_readlane_b32 s24, v245, 11
	v_lshl_add_u64 v[146:147], s[18:19], 0, v[146:147]
	v_readlane_b32 s25, v245, 12
	v_readlane_b32 s26, v245, 13
	v_readlane_b32 s27, v245, 14
	v_readlane_b32 s28, v245, 15
	v_readlane_b32 s29, v245, 16
	v_readlane_b32 s30, v245, 17
	v_readlane_b32 s31, v245, 18
	v_readlane_b32 s17, v244, 29
	v_readlane_b32 s20, v244, 32
	v_readlane_b32 s21, v244, 33
	v_readlane_b32 s22, v244, 34
	v_readlane_b32 s23, v244, 35
	s_waitcnt vmcnt(0)
	v_pk_fma_f32 v[126:127], v[126:127], 0.5, v[156:157] op_sel_hi:[1,0,1]
	v_pk_fma_f32 v[124:125], v[124:125], 0.5, v[154:155] op_sel_hi:[1,0,1]
	v_pk_fma_f32 v[122:123], v[122:123], 0.5, v[160:161] op_sel_hi:[1,0,1]
	v_pk_fma_f32 v[120:121], v[120:121], 0.5, v[158:159] op_sel_hi:[1,0,1]
	global_store_dwordx4 v[146:147], v[124:127], off
	global_store_dwordx4 v[146:147], v[120:123], off offset:16
	global_load_dwordx4 v[120:123], v[148:149], off offset:512 nt
	s_nop 0
	global_load_dwordx4 v[124:127], v[148:149], off offset:528 nt
	v_add_co_u32_e32 v154, vcc, s83, v148
	s_waitcnt vmcnt(1)
	v_pk_fma_f32 v[114:115], v[114:115], 0.5, v[122:123] op_sel_hi:[1,0,1]
	v_pk_fma_f32 v[112:113], v[112:113], 0.5, v[120:121] op_sel_hi:[1,0,1]
	v_addc_co_u32_e32 v155, vcc, 0, v149, vcc
	s_waitcnt vmcnt(0)
	v_pk_fma_f32 v[110:111], v[110:111], 0.5, v[126:127] op_sel_hi:[1,0,1]
	v_pk_fma_f32 v[108:109], v[108:109], 0.5, v[124:125] op_sel_hi:[1,0,1]
	global_store_dwordx4 v[146:147], v[112:115], off offset:512
	global_store_dwordx4 v[146:147], v[108:111], off offset:528
	global_load_dwordx4 v[108:111], v[154:155], off nt
	v_lshl_add_u64 v[112:113], v[148:149], 0, s[88:89]
	global_load_dwordx4 v[112:115], v[112:113], off offset:16 nt
	v_add_co_u32_e32 v122, vcc, s83, v146
	v_lshl_add_u64 v[120:121], v[146:147], 0, s[88:89]
	s_nop 0
	v_addc_co_u32_e32 v123, vcc, 0, v147, vcc
	s_waitcnt vmcnt(1)
	v_pk_fma_f32 v[110:111], v[118:119], 0.5, v[110:111] op_sel_hi:[1,0,1]
	v_pk_fma_f32 v[108:109], v[116:117], 0.5, v[108:109] op_sel_hi:[1,0,1]
	s_waitcnt vmcnt(0)
	v_pk_fma_f32 v[106:107], v[106:107], 0.5, v[114:115] op_sel_hi:[1,0,1]
	v_pk_fma_f32 v[104:105], v[104:105], 0.5, v[112:113] op_sel_hi:[1,0,1]
	global_store_dwordx4 v[122:123], v[108:111], off
	global_store_dwordx4 v[120:121], v[104:107], off offset:16
	global_load_dwordx4 v[104:107], v[154:155], off offset:512 nt
	v_lshl_add_u64 v[108:109], v[148:149], 0, s[90:91]
	global_load_dwordx4 v[108:111], v[108:109], off offset:16 nt
	v_add_co_u32_e32 v114, vcc, s13, v148
	v_lshl_add_u64 v[112:113], v[146:147], 0, s[90:91]
	s_nop 0
	v_addc_co_u32_e32 v115, vcc, 0, v149, vcc
	s_waitcnt vmcnt(1)
	v_pk_fma_f32 v[98:99], v[98:99], 0.5, v[106:107] op_sel_hi:[1,0,1]
	v_pk_fma_f32 v[96:97], v[96:97], 0.5, v[104:105] op_sel_hi:[1,0,1]
	s_waitcnt vmcnt(0)
	v_pk_fma_f32 v[94:95], v[94:95], 0.5, v[110:111] op_sel_hi:[1,0,1]
	v_pk_fma_f32 v[92:93], v[92:93], 0.5, v[108:109] op_sel_hi:[1,0,1]
	global_store_dwordx4 v[122:123], v[96:99], off offset:512
	global_store_dwordx4 v[112:113], v[92:95], off offset:16
	global_load_dwordx4 v[92:95], v[114:115], off nt
	v_lshl_add_u64 v[96:97], v[148:149], 0, s[92:93]
	global_load_dwordx4 v[96:99], v[96:97], off offset:16 nt
	v_add_co_u32_e32 v106, vcc, s13, v146
	v_lshl_add_u64 v[104:105], v[146:147], 0, s[92:93]
	s_nop 0
	v_addc_co_u32_e32 v107, vcc, 0, v147, vcc
	s_waitcnt vmcnt(1)
	v_pk_fma_f32 v[94:95], v[102:103], 0.5, v[94:95] op_sel_hi:[1,0,1]
	v_pk_fma_f32 v[92:93], v[100:101], 0.5, v[92:93] op_sel_hi:[1,0,1]
	s_waitcnt vmcnt(0)
	v_pk_fma_f32 v[90:91], v[90:91], 0.5, v[98:99] op_sel_hi:[1,0,1]
	v_pk_fma_f32 v[88:89], v[88:89], 0.5, v[96:97] op_sel_hi:[1,0,1]
	global_store_dwordx4 v[106:107], v[92:95], off
	global_store_dwordx4 v[104:105], v[88:91], off offset:16
	global_load_dwordx4 v[88:91], v[114:115], off offset:512 nt
	v_lshl_add_u64 v[92:93], v[148:149], 0, s[94:95]
	global_load_dwordx4 v[92:95], v[92:93], off offset:16 nt
	v_add_co_u32_e32 v98, vcc, s33, v148
	v_lshl_add_u64 v[96:97], v[146:147], 0, s[94:95]
	s_nop 0
	v_addc_co_u32_e32 v99, vcc, 0, v149, vcc
	s_waitcnt vmcnt(1)
	v_pk_fma_f32 v[82:83], v[82:83], 0.5, v[90:91] op_sel_hi:[1,0,1]
	v_pk_fma_f32 v[80:81], v[80:81], 0.5, v[88:89] op_sel_hi:[1,0,1]
	s_waitcnt vmcnt(0)
	v_pk_fma_f32 v[78:79], v[78:79], 0.5, v[94:95] op_sel_hi:[1,0,1]
	v_pk_fma_f32 v[76:77], v[76:77], 0.5, v[92:93] op_sel_hi:[1,0,1]
	global_store_dwordx4 v[106:107], v[80:83], off offset:512
	global_store_dwordx4 v[96:97], v[76:79], off offset:16
	global_load_dwordx4 v[76:79], v[98:99], off nt
	v_lshl_add_u64 v[80:81], v[148:149], 0, s[4:5]
	global_load_dwordx4 v[80:83], v[80:81], off offset:16 nt
	v_add_co_u32_e32 v90, vcc, s33, v146
	v_lshl_add_u64 v[88:89], v[146:147], 0, s[4:5]
	s_nop 0
	v_addc_co_u32_e32 v91, vcc, 0, v147, vcc
	s_waitcnt vmcnt(1)
	v_pk_fma_f32 v[78:79], v[86:87], 0.5, v[78:79] op_sel_hi:[1,0,1]
	v_pk_fma_f32 v[76:77], v[84:85], 0.5, v[76:77] op_sel_hi:[1,0,1]
	s_waitcnt vmcnt(0)
; #define PG8_BAR __builtin_amdgcn_s_barrier()
; template <class Epi, class Sched, bool ALIGN_EPI = true, bool SP2 = true>
; __device__ __forceinline__ void gemm_phase(LAS unsigned char* lds, const bf16_t* Ag, const bf16_t* Btg, const int K, const int lda, const int ldb, const Sched& S, const Epi& E) {
;     ...
;         if (!has_next) break;
; #pragma unroll
;         for (int a = 0; a < 2; ++a)
; #pragma unroll
;             for (int b = 0; b < 2; ++b)
; #pragma unroll
;                 for (int m = 0; m < 4; ++m)
; #pragma unroll
;                     for (int n = 0; n < 2; ++n) acc[a][b][m][n] = (f32x4){0.f, 0.f, 0.f, 0.f};
;         cur = nxt; cA = nA; cB = nB; ++ui;
;         if constexpr (ALIGN_EPI) { if (wr == 1) PG8_BAR; }
;     __device__ __forceinline__ void operator()(Acc& acc, const Unit& u, int wr, int wc, int fr, int fq) const {
;     ...
;         for (int ai = 0; ai < 2; ++ai)
; #pragma unroll
;             for (int m = 0; m < 4; ++m)
; #pragma unroll
;                 for (int bj = 0; bj < 2; ++bj) {
;                     const size_t p = p0 + (size_t)(ai * 128 + m * 16) * D + bj * 128;
;                     const f32x4 r0 = *(const f32x4*)(R + p), r1 = *(const f32x4*)(R + p + 4);
;                     *(f32x4*)(O + p) = r0 + acc[ai][bj][m][0] * scale; *(f32x4*)(O + p + 4) = r1 + acc[ai][bj][m][1] * scale;
;                 }
	v_pk_fma_f32 v[74:75], v[74:75], 0.5, v[82:83] op_sel_hi:[1,0,1]
	v_pk_fma_f32 v[72:73], v[72:73], 0.5, v[80:81] op_sel_hi:[1,0,1]
	global_store_dwordx4 v[90:91], v[76:79], off
	global_store_dwordx4 v[88:89], v[72:75], off offset:16
	global_load_dwordx4 v[72:75], v[98:99], off offset:512 nt
	v_lshl_add_u64 v[76:77], v[148:149], 0, s[86:87]
	global_load_dwordx4 v[76:79], v[76:77], off offset:16 nt
	v_add_co_u32_e32 v82, vcc, s96, v148
	v_lshl_add_u64 v[80:81], v[146:147], 0, s[86:87]
	s_nop 0
	v_addc_co_u32_e32 v83, vcc, 0, v149, vcc
	s_waitcnt vmcnt(1)
	v_pk_fma_f32 v[70:71], v[70:71], 0.5, v[74:75] op_sel_hi:[1,0,1]
	v_pk_fma_f32 v[68:69], v[68:69], 0.5, v[72:73] op_sel_hi:[1,0,1]
	s_waitcnt vmcnt(0)
	v_pk_fma_f32 v[66:67], v[66:67], 0.5, v[78:79] op_sel_hi:[1,0,1]
	v_pk_fma_f32 v[64:65], v[64:65], 0.5, v[76:77] op_sel_hi:[1,0,1]
	global_store_dwordx4 v[90:91], v[68:71], off offset:512
	global_store_dwordx4 v[80:81], v[64:67], off offset:16
	global_load_dwordx4 v[64:67], v[82:83], off nt
	v_lshl_add_u64 v[68:69], v[148:149], 0, s[0:1]
	global_load_dwordx4 v[68:71], v[68:69], off offset:16 nt
	v_add_co_u32_e32 v74, vcc, s96, v146
	v_lshl_add_u64 v[72:73], v[146:147], 0, s[0:1]
	s_nop 0
	v_addc_co_u32_e32 v75, vcc, 0, v147, vcc
	s_mov_b64 s[0:1], 0x160000
	s_waitcnt vmcnt(1)
	v_pk_fma_f32 v[62:63], v[62:63], 0.5, v[66:67] op_sel_hi:[1,0,1]
	v_pk_fma_f32 v[60:61], v[60:61], 0.5, v[64:65] op_sel_hi:[1,0,1]
	s_waitcnt vmcnt(0)
	v_pk_fma_f32 v[58:59], v[58:59], 0.5, v[70:71] op_sel_hi:[1,0,1]
	v_pk_fma_f32 v[56:57], v[56:57], 0.5, v[68:69] op_sel_hi:[1,0,1]
	global_store_dwordx4 v[74:75], v[60:63], off
	global_store_dwordx4 v[72:73], v[56:59], off offset:16
	global_load_dwordx4 v[56:59], v[82:83], off offset:512 nt
	v_lshl_add_u64 v[60:61], v[148:149], 0, s[34:35]
	global_load_dwordx4 v[60:63], v[60:61], off offset:16 nt
	v_add_co_u32_e32 v66, vcc, s97, v148
	v_lshl_add_u64 v[64:65], v[146:147], 0, s[34:35]
	s_nop 0
	v_addc_co_u32_e32 v67, vcc, 0, v149, vcc
	s_waitcnt vmcnt(1)
	v_pk_fma_f32 v[50:51], v[50:51], 0.5, v[58:59] op_sel_hi:[1,0,1]
	v_pk_fma_f32 v[48:49], v[48:49], 0.5, v[56:57] op_sel_hi:[1,0,1]
	s_waitcnt vmcnt(0)
	v_pk_fma_f32 v[46:47], v[46:47], 0.5, v[62:63] op_sel_hi:[1,0,1]
	v_pk_fma_f32 v[44:45], v[44:45], 0.5, v[60:61] op_sel_hi:[1,0,1]
	global_store_dwordx4 v[74:75], v[48:51], off offset:512
	global_store_dwordx4 v[64:65], v[44:47], off offset:16
	global_load_dwordx4 v[44:47], v[66:67], off nt
	v_lshl_add_u64 v[48:49], v[148:149], 0, s[38:39]
	global_load_dwordx4 v[48:51], v[48:49], off offset:16 nt
	v_add_co_u32_e32 v58, vcc, s97, v146
	v_lshl_add_u64 v[56:57], v[146:147], 0, s[38:39]
	s_nop 0
	v_addc_co_u32_e32 v59, vcc, 0, v147, vcc
	s_waitcnt vmcnt(1)
	v_pk_fma_f32 v[46:47], v[54:55], 0.5, v[46:47] op_sel_hi:[1,0,1]
	v_pk_fma_f32 v[44:45], v[52:53], 0.5, v[44:45] op_sel_hi:[1,0,1]
	s_waitcnt vmcnt(0)
	v_pk_fma_f32 v[42:43], v[42:43], 0.5, v[50:51] op_sel_hi:[1,0,1]
	v_pk_fma_f32 v[40:41], v[40:41], 0.5, v[48:49] op_sel_hi:[1,0,1]
	global_store_dwordx4 v[58:59], v[44:47], off
	global_store_dwordx4 v[56:57], v[40:43], off offset:16
	global_load_dwordx4 v[40:43], v[66:67], off offset:512 nt
	v_lshl_add_u64 v[44:45], v[148:149], 0, s[50:51]
	global_load_dwordx4 v[44:47], v[44:45], off offset:16 nt
	v_add_co_u32_e32 v50, vcc, s8, v148
	v_lshl_add_u64 v[48:49], v[146:147], 0, s[50:51]
	s_nop 0
	v_addc_co_u32_e32 v51, vcc, 0, v149, vcc
	s_waitcnt vmcnt(1)
	v_pk_fma_f32 v[34:35], v[34:35], 0.5, v[42:43] op_sel_hi:[1,0,1]
	v_pk_fma_f32 v[32:33], v[32:33], 0.5, v[40:41] op_sel_hi:[1,0,1]
	s_waitcnt vmcnt(0)
	v_pk_fma_f32 v[30:31], v[30:31], 0.5, v[46:47] op_sel_hi:[1,0,1]
	v_pk_fma_f32 v[28:29], v[28:29], 0.5, v[44:45] op_sel_hi:[1,0,1]
	global_store_dwordx4 v[58:59], v[32:35], off offset:512
	global_store_dwordx4 v[48:49], v[28:31], off offset:16
	global_load_dwordx4 v[28:31], v[50:51], off nt
	v_lshl_add_u64 v[32:33], v[148:149], 0, s[52:53]
	global_load_dwordx4 v[32:35], v[32:33], off offset:16 nt
	v_add_co_u32_e32 v42, vcc, s8, v146
	v_lshl_add_u64 v[40:41], v[146:147], 0, s[52:53]
	s_nop 0
	v_addc_co_u32_e32 v43, vcc, 0, v147, vcc
	s_waitcnt vmcnt(1)
	v_pk_fma_f32 v[30:31], v[38:39], 0.5, v[30:31] op_sel_hi:[1,0,1]
	v_pk_fma_f32 v[28:29], v[36:37], 0.5, v[28:29] op_sel_hi:[1,0,1]
	s_waitcnt vmcnt(0)
	v_pk_fma_f32 v[26:27], v[26:27], 0.5, v[34:35] op_sel_hi:[1,0,1]
	v_pk_fma_f32 v[24:25], v[24:25], 0.5, v[32:33] op_sel_hi:[1,0,1]
	global_store_dwordx4 v[42:43], v[28:31], off
	global_store_dwordx4 v[40:41], v[24:27], off offset:16
	global_load_dwordx4 v[24:27], v[50:51], off offset:512 nt
	v_lshl_add_u64 v[28:29], v[148:149], 0, s[54:55]
	global_load_dwordx4 v[28:31], v[28:29], off offset:16 nt
	v_add_co_u32_e32 v34, vcc, s9, v148
	v_lshl_add_u64 v[32:33], v[146:147], 0, s[54:55]
	s_nop 0
	v_addc_co_u32_e32 v35, vcc, 0, v149, vcc
	s_waitcnt vmcnt(1)
	v_pk_fma_f32 v[22:23], v[22:23], 0.5, v[26:27] op_sel_hi:[1,0,1]
	v_pk_fma_f32 v[20:21], v[20:21], 0.5, v[24:25] op_sel_hi:[1,0,1]
	s_waitcnt vmcnt(0)
	v_pk_fma_f32 v[14:15], v[14:15], 0.5, v[30:31] op_sel_hi:[1,0,1]
	v_pk_fma_f32 v[12:13], v[12:13], 0.5, v[28:29] op_sel_hi:[1,0,1]
	global_store_dwordx4 v[42:43], v[20:23], off offset:512
	global_store_dwordx4 v[32:33], v[12:15], off offset:16
	global_load_dwordx4 v[12:15], v[34:35], off nt
	v_lshl_add_u64 v[20:21], v[148:149], 0, s[0:1]
	global_load_dwordx4 v[20:23], v[20:21], off offset:16 nt
	v_add_co_u32_e32 v26, vcc, s9, v146
	v_lshl_add_u64 v[24:25], v[146:147], 0, s[0:1]
	s_nop 0
	v_addc_co_u32_e32 v27, vcc, 0, v147, vcc
	s_andn2_b64 vcc, exec, s[2:3]
	s_mov_b64 s[2:3], -1
	s_waitcnt vmcnt(1)
	v_pk_fma_f32 v[14:15], v[18:19], 0.5, v[14:15] op_sel_hi:[1,0,1]
	v_pk_fma_f32 v[12:13], v[16:17], 0.5, v[12:13] op_sel_hi:[1,0,1]
	s_waitcnt vmcnt(0)
	v_pk_fma_f32 v[10:11], v[10:11], 0.5, v[22:23] op_sel_hi:[1,0,1]
	v_pk_fma_f32 v[8:9], v[8:9], 0.5, v[20:21] op_sel_hi:[1,0,1]
	global_store_dwordx4 v[26:27], v[12:15], off
	global_store_dwordx4 v[24:25], v[8:11], off offset:16
	global_load_dwordx4 v[8:11], v[34:35], off offset:512 nt
	v_lshl_add_u64 v[12:13], v[148:149], 0, s[58:59]
	global_load_dwordx4 v[12:15], v[12:13], off offset:16 nt
	v_lshl_add_u64 v[16:17], v[146:147], 0, s[58:59]
	s_waitcnt vmcnt(1)
	v_pk_fma_f32 v[6:7], v[6:7], 0.5, v[10:11] op_sel_hi:[1,0,1]
	v_pk_fma_f32 v[4:5], v[4:5], 0.5, v[8:9] op_sel_hi:[1,0,1]
	s_waitcnt vmcnt(0)
	v_pk_fma_f32 v[2:3], v[2:3], 0.5, v[14:15] op_sel_hi:[1,0,1]
	v_pk_fma_f32 v[0:1], v[0:1], 0.5, v[12:13] op_sel_hi:[1,0,1]
	global_store_dwordx4 v[26:27], v[4:7], off offset:512
	global_store_dwordx4 v[16:17], v[0:3], off offset:16
	s_cbranch_vccnz .LBB0_191
	v_readlane_b32 s0, v244, 37
	v_readlane_b32 s1, v244, 38
	s_andn2_b64 vcc, exec, s[0:1]
	s_cbranch_vccnz .LBB0_190
	s_barrier
	s_branch .LBB0_190

;     __device__ __forceinline__ void operator()(Acc& acc, const Unit& u, int wr, int wc, int fr, int fq) const {
;         const size_t p0 = u.ooff + (size_t)(wr * 64 + fr) * D + wc * 32 + 8 * fq;
; #pragma unroll
;         for (int ai = 0; ai < 2; ++ai)
; #pragma unroll
;             for (int m = 0; m < 4; ++m)
; #pragma unroll
;                 for (int bj = 0; bj < 2; ++bj) {
;                     const size_t p = p0 + (size_t)(ai * 128 + m * 16) * D + bj * 128;
;                     const f32x4 r0 = *(const f32x4*)(R + p), r1 = *(const f32x4*)(R + p + 4);
;                     *(f32x4*)(O + p) = r0 + acc[ai][bj][m][0] * scale; *(f32x4*)(O + p + 4) = r1 + acc[ai][bj][m][1] * scale;
;                 }
.LBB0_972:
	v_lshl_add_u64 v[146:147], s[22:23], 2, v[136:137]
	global_load_dwordx4 v[152:155], v[146:147], off offset:16 nt
	global_load_dwordx4 v[156:159], v[146:147], off nt
	s_mov_b64 s[22:23], 0x20000
	s_waitcnt vmcnt(0)
	v_pk_add_f32 v[122:123], v[122:123], v[154:155]
	v_pk_add_f32 v[126:127], v[126:127], v[158:159]
	v_pk_add_f32 v[124:125], v[124:125], v[156:157]
	v_pk_add_f32 v[120:121], v[120:121], v[152:153]
	global_store_dwordx4 v[146:147], v[124:127], off
	global_store_dwordx4 v[146:147], v[120:123], off offset:16
	global_load_dwordx4 v[120:123], v[146:147], off offset:528 nt
	s_nop 0
	global_load_dwordx4 v[124:127], v[146:147], off offset:512 nt
	s_waitcnt vmcnt(1)
	v_pk_add_f32 v[106:107], v[106:107], v[122:123]
	s_waitcnt vmcnt(0)
	v_pk_add_f32 v[114:115], v[114:115], v[126:127]
	v_pk_add_f32 v[112:113], v[112:113], v[124:125]
	global_store_dwordx4 v[146:147], v[112:115], off offset:512
	v_pk_add_f32 v[104:105], v[104:105], v[120:121]
	global_store_dwordx4 v[146:147], v[104:107], off offset:528
	v_lshl_add_u64 v[112:113], v[146:147], 0, s[22:23]
	s_mov_b32 s22, 0x20000
	v_add_co_u32_e32 v120, vcc, s22, v146
	s_mov_b64 s[22:23], 0x20200
	s_nop 0
	v_addc_co_u32_e32 v121, vcc, 0, v147, vcc
	global_load_dwordx4 v[104:107], v[120:121], off nt
	s_nop 0
	global_load_dwordx4 v[112:115], v[112:113], off offset:16 nt
	s_waitcnt vmcnt(1)
	v_pk_add_f32 v[106:107], v[118:119], v[106:107]
	v_pk_add_f32 v[104:105], v[116:117], v[104:105]
	global_store_dwordx4 v[120:121], v[104:107], off
	s_waitcnt vmcnt(1)
	s_nop 0
	v_pk_add_f32 v[106:107], v[110:111], v[114:115]
	v_pk_add_f32 v[104:105], v[108:109], v[112:113]
	global_store_dwordx4 v[120:121], v[104:107], off offset:16
	v_lshl_add_u64 v[108:109], v[146:147], 0, s[22:23]
	global_load_dwordx4 v[104:107], v[120:121], off offset:512 nt
	s_nop 0
	global_load_dwordx4 v[108:111], v[108:109], off offset:16 nt
	s_mov_b64 s[22:23], 0x40000
	s_waitcnt vmcnt(1)
	v_pk_add_f32 v[102:103], v[102:103], v[106:107]
	v_pk_add_f32 v[100:101], v[100:101], v[104:105]
	global_store_dwordx4 v[120:121], v[100:103], off offset:512
	s_waitcnt vmcnt(1)
	v_pk_add_f32 v[98:99], v[98:99], v[110:111]
	v_pk_add_f32 v[96:97], v[96:97], v[108:109]
	v_lshl_add_u64 v[100:101], v[146:147], 0, s[22:23]
	s_mov_b32 s22, 0x40000
	v_add_co_u32_e32 v104, vcc, s22, v146
	global_store_dwordx4 v[120:121], v[96:99], off offset:528
	s_nop 0
	v_addc_co_u32_e32 v105, vcc, 0, v147, vcc
	global_load_dwordx4 v[96:99], v[104:105], off nt
	s_nop 0
	global_load_dwordx4 v[100:103], v[100:101], off offset:16 nt
	s_mov_b64 s[22:23], 0x40200
	s_waitcnt vmcnt(1)
	v_pk_add_f32 v[94:95], v[94:95], v[98:99]
	v_pk_add_f32 v[92:93], v[92:93], v[96:97]
	s_waitcnt vmcnt(0)
	v_pk_add_f32 v[90:91], v[90:91], v[102:103]
	v_pk_add_f32 v[88:89], v[88:89], v[100:101]
	global_store_dwordx4 v[104:105], v[92:95], off
	global_store_dwordx4 v[104:105], v[88:91], off offset:16
	s_nop 0
	v_lshl_add_u64 v[92:93], v[146:147], 0, s[22:23]
	global_load_dwordx4 v[88:91], v[104:105], off offset:512 nt
	s_nop 0
	global_load_dwordx4 v[92:95], v[92:93], off offset:16 nt
	s_mov_b64 s[22:23], 0x60000
	s_waitcnt vmcnt(1)
	v_pk_add_f32 v[86:87], v[86:87], v[90:91]
	v_pk_add_f32 v[84:85], v[84:85], v[88:89]
	global_store_dwordx4 v[104:105], v[84:87], off offset:512
	s_waitcnt vmcnt(1)
	v_pk_add_f32 v[82:83], v[82:83], v[94:95]
	v_pk_add_f32 v[80:81], v[80:81], v[92:93]
	v_lshl_add_u64 v[84:85], v[146:147], 0, s[22:23]
	s_mov_b32 s22, 0x60000
	v_add_co_u32_e32 v88, vcc, s22, v146
	global_store_dwordx4 v[104:105], v[80:83], off offset:528
	s_nop 0
	v_addc_co_u32_e32 v89, vcc, 0, v147, vcc
	global_load_dwordx4 v[80:83], v[88:89], off nt
	s_nop 0
	global_load_dwordx4 v[84:87], v[84:85], off offset:16 nt
	s_mov_b64 s[22:23], 0x60200
	s_waitcnt vmcnt(1)
	v_pk_add_f32 v[78:79], v[78:79], v[82:83]
	v_pk_add_f32 v[76:77], v[76:77], v[80:81]
	s_waitcnt vmcnt(0)
	v_pk_add_f32 v[74:75], v[74:75], v[86:87]
	v_pk_add_f32 v[72:73], v[72:73], v[84:85]
	global_store_dwordx4 v[88:89], v[76:79], off
	global_store_dwordx4 v[88:89], v[72:75], off offset:16
	s_nop 0
	v_lshl_add_u64 v[76:77], v[146:147], 0, s[22:23]
	global_load_dwordx4 v[72:75], v[88:89], off offset:512 nt
	s_nop 0
	global_load_dwordx4 v[76:79], v[76:77], off offset:16 nt
	s_mov_b64 s[22:23], 0x100000
	s_waitcnt vmcnt(1)
	v_pk_add_f32 v[70:71], v[70:71], v[74:75]
	v_pk_add_f32 v[68:69], v[68:69], v[72:73]
	global_store_dwordx4 v[88:89], v[68:71], off offset:512
	s_waitcnt vmcnt(1)
; #define PG8_BAR __builtin_amdgcn_s_barrier()
; template <class Epi, class Sched, bool ALIGN_EPI = true, bool SP2 = true>
; __device__ __forceinline__ void gemm_phase(LAS unsigned char* lds, const bf16_t* Ag, const bf16_t* Btg, const int K, const int lda, const int ldb, const Sched& S, const Epi& E) {
;     ...
;         if (!has_next) break;
; #pragma unroll
;         for (int a = 0; a < 2; ++a)
; #pragma unroll
;             for (int b = 0; b < 2; ++b)
; #pragma unroll
;                 for (int m = 0; m < 4; ++m)
; #pragma unroll
;                     for (int n = 0; n < 2; ++n) acc[a][b][m][n] = (f32x4){0.f, 0.f, 0.f, 0.f};
;         cur = nxt; cA = nA; cB = nB; ++ui;
;         if constexpr (ALIGN_EPI) { if (wr == 1) PG8_BAR; }
;     __device__ __forceinline__ void operator()(Acc& acc, const Unit& u, int wr, int wc, int fr, int fq) const {
;         const size_t p0 = u.ooff + (size_t)(wr * 64 + fr) * D + wc * 32 + 8 * fq;
; #pragma unroll
;         for (int ai = 0; ai < 2; ++ai)
; #pragma unroll
;             for (int m = 0; m < 4; ++m)
; #pragma unroll
;                 for (int bj = 0; bj < 2; ++bj) {
;                     const size_t p = p0 + (size_t)(ai * 128 + m * 16) * D + bj * 128;
;                     const f32x4 r0 = *(const f32x4*)(R + p), r1 = *(const f32x4*)(R + p + 4);
;                     *(f32x4*)(O + p) = r0 + acc[ai][bj][m][0] * scale; *(f32x4*)(O + p + 4) = r1 + acc[ai][bj][m][1] * scale;
;                 }
	v_pk_add_f32 v[66:67], v[66:67], v[78:79]
	v_pk_add_f32 v[64:65], v[64:65], v[76:77]
	v_lshl_add_u64 v[68:69], v[146:147], 0, s[22:23]
	s_mov_b32 s22, 0x100000
	v_add_co_u32_e32 v72, vcc, s22, v146
	global_store_dwordx4 v[88:89], v[64:67], off offset:528
	s_nop 0
	v_addc_co_u32_e32 v73, vcc, 0, v147, vcc
	global_load_dwordx4 v[64:67], v[72:73], off nt
	s_nop 0
	global_load_dwordx4 v[68:71], v[68:69], off offset:16 nt
	s_mov_b64 s[22:23], 0x100200
	s_waitcnt vmcnt(1)
	v_pk_add_f32 v[62:63], v[62:63], v[66:67]
	v_pk_add_f32 v[60:61], v[60:61], v[64:65]
	s_waitcnt vmcnt(0)
	v_pk_add_f32 v[58:59], v[58:59], v[70:71]
	v_pk_add_f32 v[56:57], v[56:57], v[68:69]
	global_store_dwordx4 v[72:73], v[60:63], off
	global_store_dwordx4 v[72:73], v[56:59], off offset:16
	s_nop 0
	v_lshl_add_u64 v[60:61], v[146:147], 0, s[22:23]
	global_load_dwordx4 v[56:59], v[72:73], off offset:512 nt
	s_nop 0
	global_load_dwordx4 v[60:63], v[60:61], off offset:16 nt
	s_mov_b64 s[22:23], 0x120000
	s_waitcnt vmcnt(1)
	v_pk_add_f32 v[54:55], v[54:55], v[58:59]
	v_pk_add_f32 v[52:53], v[52:53], v[56:57]
	global_store_dwordx4 v[72:73], v[52:55], off offset:512
	s_waitcnt vmcnt(1)
	v_pk_add_f32 v[50:51], v[50:51], v[62:63]
	v_pk_add_f32 v[48:49], v[48:49], v[60:61]
	v_lshl_add_u64 v[52:53], v[146:147], 0, s[22:23]
	s_mov_b32 s22, 0x120000
	v_add_co_u32_e32 v56, vcc, s22, v146
	global_store_dwordx4 v[72:73], v[48:51], off offset:528
	s_nop 0
	v_addc_co_u32_e32 v57, vcc, 0, v147, vcc
	global_load_dwordx4 v[48:51], v[56:57], off nt
	s_nop 0
	global_load_dwordx4 v[52:55], v[52:53], off offset:16 nt
	s_mov_b64 s[22:23], 0x120200
	s_waitcnt vmcnt(1)
	v_pk_add_f32 v[46:47], v[46:47], v[50:51]
	v_pk_add_f32 v[44:45], v[44:45], v[48:49]
	s_waitcnt vmcnt(0)
	v_pk_add_f32 v[42:43], v[42:43], v[54:55]
	v_pk_add_f32 v[40:41], v[40:41], v[52:53]
	global_store_dwordx4 v[56:57], v[44:47], off
	global_store_dwordx4 v[56:57], v[40:43], off offset:16
	s_nop 0
	v_lshl_add_u64 v[44:45], v[146:147], 0, s[22:23]
	global_load_dwordx4 v[40:43], v[56:57], off offset:512 nt
	s_nop 0
	global_load_dwordx4 v[44:47], v[44:45], off offset:16 nt
	s_mov_b64 s[22:23], 0x140000
	s_waitcnt vmcnt(1)
	v_pk_add_f32 v[38:39], v[38:39], v[42:43]
	v_pk_add_f32 v[36:37], v[36:37], v[40:41]
	global_store_dwordx4 v[56:57], v[36:39], off offset:512
	s_waitcnt vmcnt(1)
	v_pk_add_f32 v[34:35], v[34:35], v[46:47]
	v_pk_add_f32 v[32:33], v[32:33], v[44:45]
	v_lshl_add_u64 v[36:37], v[146:147], 0, s[22:23]
	s_mov_b32 s22, 0x140000
	v_add_co_u32_e32 v40, vcc, s22, v146
	global_store_dwordx4 v[56:57], v[32:35], off offset:528
	s_nop 0
	v_addc_co_u32_e32 v41, vcc, 0, v147, vcc
	global_load_dwordx4 v[32:35], v[40:41], off nt
	s_nop 0
	global_load_dwordx4 v[36:39], v[36:37], off offset:16 nt
	s_mov_b64 s[22:23], 0x140200
	s_waitcnt vmcnt(1)
	v_pk_add_f32 v[30:31], v[30:31], v[34:35]
	v_pk_add_f32 v[28:29], v[28:29], v[32:33]
	s_waitcnt vmcnt(0)
	v_pk_add_f32 v[26:27], v[26:27], v[38:39]
	v_pk_add_f32 v[24:25], v[24:25], v[36:37]
	global_store_dwordx4 v[40:41], v[28:31], off
	global_store_dwordx4 v[40:41], v[24:27], off offset:16
	s_nop 0
	v_lshl_add_u64 v[28:29], v[146:147], 0, s[22:23]
	global_load_dwordx4 v[24:27], v[40:41], off offset:512 nt
	s_nop 0
	global_load_dwordx4 v[28:31], v[28:29], off offset:16 nt
	s_mov_b64 s[22:23], 0x160000
	s_waitcnt vmcnt(1)
	v_pk_add_f32 v[22:23], v[22:23], v[26:27]
	s_waitcnt vmcnt(0)
	v_pk_add_f32 v[18:19], v[18:19], v[30:31]
	v_pk_add_f32 v[16:17], v[16:17], v[28:29]
	v_pk_add_f32 v[20:21], v[20:21], v[24:25]
	global_store_dwordx4 v[40:41], v[16:19], off offset:528
	global_store_dwordx4 v[40:41], v[20:23], off offset:512
	s_nop 0
	v_add_co_u32_e32 v16, vcc, s46, v146
	v_lshl_add_u64 v[22:23], v[146:147], 0, s[22:23]
	s_nop 0
	v_addc_co_u32_e32 v17, vcc, 0, v147, vcc
	global_load_dwordx4 v[18:21], v[16:17], off nt
	s_nop 0
	global_load_dwordx4 v[22:25], v[22:23], off offset:16 nt
	s_mov_b64 s[22:23], -1
	s_andn2_b64 vcc, exec, s[2:3]
	s_waitcnt vmcnt(1)
	v_pk_add_f32 v[14:15], v[14:15], v[20:21]
	v_pk_add_f32 v[12:13], v[12:13], v[18:19]
	s_waitcnt vmcnt(0)
	v_pk_add_f32 v[10:11], v[10:11], v[24:25]
	v_pk_add_f32 v[8:9], v[8:9], v[22:23]
	global_store_dwordx4 v[16:17], v[12:15], off
	global_store_dwordx4 v[16:17], v[8:11], off offset:16
	s_nop 1
	v_lshl_add_u64 v[8:9], v[146:147], 0, s[10:11]
	global_load_dwordx4 v[12:15], v[16:17], off offset:512 nt
	s_nop 0
	global_load_dwordx4 v[8:11], v[8:9], off offset:16 nt
	s_waitcnt vmcnt(1)
	v_pk_add_f32 v[6:7], v[6:7], v[14:15]
	v_pk_add_f32 v[4:5], v[4:5], v[12:13]
	s_waitcnt vmcnt(0)
	v_pk_add_f32 v[2:3], v[2:3], v[10:11]
	v_pk_add_f32 v[0:1], v[0:1], v[8:9]
	global_store_dwordx4 v[16:17], v[4:7], off offset:512
	global_store_dwordx4 v[16:17], v[0:3], off offset:528
	s_cbranch_vccnz .LBB0_961
	s_andn2_b64 vcc, exec, s[4:5]
	s_cbranch_vccnz .LBB0_960
	s_barrier
	s_branch .LBB0_960

;     __device__ __forceinline__ void operator()(Acc& acc, const Unit& u, int wr, int wc, int fr, int fq) const {
;         const size_t p0 = u.ooff + (size_t)(wr * 64 + fr) * D + wc * 32 + 8 * fq;
; #pragma unroll
;         for (int ai = 0; ai < 2; ++ai)
; #pragma unroll
;             for (int m = 0; m < 4; ++m)
; #pragma unroll
;                 for (int bj = 0; bj < 2; ++bj) {
;                     const size_t p = p0 + (size_t)(ai * 128 + m * 16) * D + bj * 128;
;                     const f32x4 r0 = *(const f32x4*)(R + p), r1 = *(const f32x4*)(R + p + 4);
;                     *(f32x4*)(O + p) = r0 + acc[ai][bj][m][0] * scale; *(f32x4*)(O + p + 4) = r1 + acc[ai][bj][m][1] * scale;
;                 }
.LBB0_1239:
	v_lshl_add_u64 v[146:147], s[38:39], 2, v[136:137]
	global_load_dwordx4 v[152:155], v[146:147], off offset:16 nt
	global_load_dwordx4 v[156:159], v[146:147], off nt
	s_mov_b32 s33, 0x20000
	s_mov_b64 s[38:39], 0x20000
	s_waitcnt vmcnt(0)
	v_pk_add_f32 v[122:123], v[122:123], v[154:155]
	v_pk_add_f32 v[126:127], v[126:127], v[158:159]
	v_pk_add_f32 v[124:125], v[124:125], v[156:157]
	v_pk_add_f32 v[120:121], v[120:121], v[152:153]
	global_store_dwordx4 v[146:147], v[124:127], off
	global_store_dwordx4 v[146:147], v[120:123], off offset:16
	global_load_dwordx4 v[120:123], v[146:147], off offset:528 nt
	s_nop 0
	global_load_dwordx4 v[124:127], v[146:147], off offset:512 nt
	s_waitcnt vmcnt(1)
	v_pk_add_f32 v[106:107], v[106:107], v[122:123]
	s_waitcnt vmcnt(0)
	v_pk_add_f32 v[114:115], v[114:115], v[126:127]
	v_pk_add_f32 v[112:113], v[112:113], v[124:125]
	v_pk_add_f32 v[104:105], v[104:105], v[120:121]
	v_add_co_u32_e32 v120, vcc, s33, v146
	global_store_dwordx4 v[146:147], v[112:115], off offset:512
	global_store_dwordx4 v[146:147], v[104:107], off offset:528
	v_addc_co_u32_e32 v121, vcc, 0, v147, vcc
	v_lshl_add_u64 v[112:113], v[146:147], 0, s[38:39]
	global_load_dwordx4 v[104:107], v[120:121], off nt
	s_nop 0
	global_load_dwordx4 v[112:115], v[112:113], off offset:16 nt
	s_mov_b64 s[38:39], 0x20200
	s_mov_b32 s33, 0x40000
	s_waitcnt vmcnt(1)
	v_pk_add_f32 v[106:107], v[118:119], v[106:107]
	v_pk_add_f32 v[104:105], v[116:117], v[104:105]
	global_store_dwordx4 v[120:121], v[104:107], off
	s_waitcnt vmcnt(1)
	s_nop 0
	v_pk_add_f32 v[106:107], v[110:111], v[114:115]
	v_pk_add_f32 v[104:105], v[108:109], v[112:113]
	global_store_dwordx4 v[120:121], v[104:107], off offset:16
	v_lshl_add_u64 v[108:109], v[146:147], 0, s[38:39]
	global_load_dwordx4 v[104:107], v[120:121], off offset:512 nt
	s_nop 0
	global_load_dwordx4 v[108:111], v[108:109], off offset:16 nt
	s_mov_b64 s[38:39], 0x40000
	s_waitcnt vmcnt(1)
	v_pk_add_f32 v[102:103], v[102:103], v[106:107]
	v_pk_add_f32 v[100:101], v[100:101], v[104:105]
	s_waitcnt vmcnt(0)
	v_pk_add_f32 v[98:99], v[98:99], v[110:111]
	v_pk_add_f32 v[96:97], v[96:97], v[108:109]
	v_add_co_u32_e32 v104, vcc, s33, v146
	global_store_dwordx4 v[120:121], v[100:103], off offset:512
	global_store_dwordx4 v[120:121], v[96:99], off offset:528
	v_addc_co_u32_e32 v105, vcc, 0, v147, vcc
	v_lshl_add_u64 v[100:101], v[146:147], 0, s[38:39]
	global_load_dwordx4 v[96:99], v[104:105], off nt
	s_nop 0
	global_load_dwordx4 v[100:103], v[100:101], off offset:16 nt
	s_mov_b64 s[38:39], 0x40200
	s_mov_b32 s33, 0x60000
	s_waitcnt vmcnt(1)
	v_pk_add_f32 v[94:95], v[94:95], v[98:99]
	v_pk_add_f32 v[92:93], v[92:93], v[96:97]
	s_waitcnt vmcnt(0)
	v_pk_add_f32 v[90:91], v[90:91], v[102:103]
	v_pk_add_f32 v[88:89], v[88:89], v[100:101]
	global_store_dwordx4 v[104:105], v[92:95], off
	global_store_dwordx4 v[104:105], v[88:91], off offset:16
	s_nop 0
	v_lshl_add_u64 v[92:93], v[146:147], 0, s[38:39]
	global_load_dwordx4 v[88:91], v[104:105], off offset:512 nt
	s_nop 0
	global_load_dwordx4 v[92:95], v[92:93], off offset:16 nt
	s_mov_b64 s[38:39], 0x60000
	s_waitcnt vmcnt(1)
	v_pk_add_f32 v[86:87], v[86:87], v[90:91]
	v_pk_add_f32 v[84:85], v[84:85], v[88:89]
	s_waitcnt vmcnt(0)
	v_pk_add_f32 v[82:83], v[82:83], v[94:95]
	v_pk_add_f32 v[80:81], v[80:81], v[92:93]
	v_add_co_u32_e32 v88, vcc, s33, v146
	global_store_dwordx4 v[104:105], v[84:87], off offset:512
	global_store_dwordx4 v[104:105], v[80:83], off offset:528
	v_addc_co_u32_e32 v89, vcc, 0, v147, vcc
	v_lshl_add_u64 v[84:85], v[146:147], 0, s[38:39]
	global_load_dwordx4 v[80:83], v[88:89], off nt
	s_nop 0
	global_load_dwordx4 v[84:87], v[84:85], off offset:16 nt
	s_mov_b64 s[38:39], 0x60200
	s_mov_b32 s33, 0x100000
	s_waitcnt vmcnt(1)
	v_pk_add_f32 v[78:79], v[78:79], v[82:83]
	v_pk_add_f32 v[76:77], v[76:77], v[80:81]
	s_waitcnt vmcnt(0)
	v_pk_add_f32 v[74:75], v[74:75], v[86:87]
	v_pk_add_f32 v[72:73], v[72:73], v[84:85]
	global_store_dwordx4 v[88:89], v[76:79], off
	global_store_dwordx4 v[88:89], v[72:75], off offset:16
	s_nop 0
	v_lshl_add_u64 v[76:77], v[146:147], 0, s[38:39]
	global_load_dwordx4 v[72:75], v[88:89], off offset:512 nt
	s_nop 0
	global_load_dwordx4 v[76:79], v[76:77], off offset:16 nt
	s_mov_b64 s[38:39], 0x100000
	s_waitcnt vmcnt(1)
	v_pk_add_f32 v[70:71], v[70:71], v[74:75]
	v_pk_add_f32 v[68:69], v[68:69], v[72:73]
	s_waitcnt vmcnt(0)
; #define PG8_BAR __builtin_amdgcn_s_barrier()
; template <class Epi, class Sched, bool ALIGN_EPI = true, bool SP2 = true>
; __device__ __forceinline__ void gemm_phase(LAS unsigned char* lds, const bf16_t* Ag, const bf16_t* Btg, const int K, const int lda, const int ldb, const Sched& S, const Epi& E) {
;     ...
;         if (!has_next) break;
; #pragma unroll
;         for (int a = 0; a < 2; ++a)
; #pragma unroll
;             for (int b = 0; b < 2; ++b)
; #pragma unroll
;                 for (int m = 0; m < 4; ++m)
; #pragma unroll
;                     for (int n = 0; n < 2; ++n) acc[a][b][m][n] = (f32x4){0.f, 0.f, 0.f, 0.f};
;         cur = nxt; cA = nA; cB = nB; ++ui;
;         if constexpr (ALIGN_EPI) { if (wr == 1) PG8_BAR; }
;     __device__ __forceinline__ void operator()(Acc& acc, const Unit& u, int wr, int wc, int fr, int fq) const {
;         const size_t p0 = u.ooff + (size_t)(wr * 64 + fr) * D + wc * 32 + 8 * fq;
; #pragma unroll
;         for (int ai = 0; ai < 2; ++ai)
; #pragma unroll
;             for (int m = 0; m < 4; ++m)
; #pragma unroll
;                 for (int bj = 0; bj < 2; ++bj) {
;                     const size_t p = p0 + (size_t)(ai * 128 + m * 16) * D + bj * 128;
;                     const f32x4 r0 = *(const f32x4*)(R + p), r1 = *(const f32x4*)(R + p + 4);
;                     *(f32x4*)(O + p) = r0 + acc[ai][bj][m][0] * scale; *(f32x4*)(O + p + 4) = r1 + acc[ai][bj][m][1] * scale;
;                 }
	v_pk_add_f32 v[66:67], v[66:67], v[78:79]
	v_pk_add_f32 v[64:65], v[64:65], v[76:77]
	v_add_co_u32_e32 v72, vcc, s33, v146
	global_store_dwordx4 v[88:89], v[68:71], off offset:512
	global_store_dwordx4 v[88:89], v[64:67], off offset:528
	v_addc_co_u32_e32 v73, vcc, 0, v147, vcc
	v_lshl_add_u64 v[68:69], v[146:147], 0, s[38:39]
	global_load_dwordx4 v[64:67], v[72:73], off nt
	s_nop 0
	global_load_dwordx4 v[68:71], v[68:69], off offset:16 nt
	s_mov_b64 s[38:39], 0x100200
	s_waitcnt vmcnt(1)
	v_pk_add_f32 v[62:63], v[62:63], v[66:67]
	v_pk_add_f32 v[60:61], v[60:61], v[64:65]
	s_waitcnt vmcnt(0)
	v_pk_add_f32 v[58:59], v[58:59], v[70:71]
	v_pk_add_f32 v[56:57], v[56:57], v[68:69]
	global_store_dwordx4 v[72:73], v[60:63], off
	global_store_dwordx4 v[72:73], v[56:59], off offset:16
	s_nop 0
	v_lshl_add_u64 v[60:61], v[146:147], 0, s[38:39]
	global_load_dwordx4 v[56:59], v[72:73], off offset:512 nt
	s_nop 0
	global_load_dwordx4 v[60:63], v[60:61], off offset:16 nt
	s_mov_b64 s[38:39], -1
	s_waitcnt vmcnt(1)
	v_pk_add_f32 v[54:55], v[54:55], v[58:59]
	v_pk_add_f32 v[52:53], v[52:53], v[56:57]
	s_waitcnt vmcnt(0)
	v_pk_add_f32 v[50:51], v[50:51], v[62:63]
	v_pk_add_f32 v[48:49], v[48:49], v[60:61]
	v_add_co_u32_e32 v56, vcc, s62, v146
	global_store_dwordx4 v[72:73], v[52:55], off offset:512
	global_store_dwordx4 v[72:73], v[48:51], off offset:528
	v_addc_co_u32_e32 v57, vcc, 0, v147, vcc
	v_lshl_add_u64 v[52:53], v[146:147], 0, s[12:13]
	global_load_dwordx4 v[48:51], v[56:57], off nt
	s_nop 0
	global_load_dwordx4 v[52:55], v[52:53], off offset:16 nt
	s_waitcnt vmcnt(1)
	v_pk_add_f32 v[46:47], v[46:47], v[50:51]
	v_pk_add_f32 v[44:45], v[44:45], v[48:49]
	s_waitcnt vmcnt(0)
	v_pk_add_f32 v[42:43], v[42:43], v[54:55]
	v_pk_add_f32 v[40:41], v[40:41], v[52:53]
	global_store_dwordx4 v[56:57], v[44:47], off
	global_store_dwordx4 v[56:57], v[40:43], off offset:16
	s_nop 0
	v_lshl_add_u64 v[44:45], v[146:147], 0, s[14:15]
	global_load_dwordx4 v[40:43], v[56:57], off offset:512 nt
	s_nop 0
	global_load_dwordx4 v[44:47], v[44:45], off offset:16 nt
	s_waitcnt vmcnt(1)
	v_pk_add_f32 v[38:39], v[38:39], v[42:43]
	v_pk_add_f32 v[36:37], v[36:37], v[40:41]
	s_waitcnt vmcnt(0)
	v_pk_add_f32 v[34:35], v[34:35], v[46:47]
	v_pk_add_f32 v[32:33], v[32:33], v[44:45]
	v_add_co_u32_e32 v40, vcc, s63, v146
	global_store_dwordx4 v[56:57], v[36:39], off offset:512
	global_store_dwordx4 v[56:57], v[32:35], off offset:528
	v_addc_co_u32_e32 v41, vcc, 0, v147, vcc
	v_lshl_add_u64 v[36:37], v[146:147], 0, s[16:17]
	global_load_dwordx4 v[32:35], v[40:41], off nt
	s_nop 0
	global_load_dwordx4 v[36:39], v[36:37], off offset:16 nt
	s_waitcnt vmcnt(1)
	v_pk_add_f32 v[30:31], v[30:31], v[34:35]
	v_pk_add_f32 v[28:29], v[28:29], v[32:33]
	s_waitcnt vmcnt(0)
	v_pk_add_f32 v[26:27], v[26:27], v[38:39]
	v_pk_add_f32 v[24:25], v[24:25], v[36:37]
	global_store_dwordx4 v[40:41], v[28:31], off
	global_store_dwordx4 v[40:41], v[24:27], off offset:16
	s_nop 0
	v_lshl_add_u64 v[28:29], v[146:147], 0, s[18:19]
	global_load_dwordx4 v[24:27], v[40:41], off offset:512 nt
	s_nop 0
	global_load_dwordx4 v[28:31], v[28:29], off offset:16 nt
	s_waitcnt vmcnt(1)
	v_pk_add_f32 v[22:23], v[22:23], v[26:27]
	s_waitcnt vmcnt(0)
	v_pk_add_f32 v[18:19], v[18:19], v[30:31]
	v_pk_add_f32 v[16:17], v[16:17], v[28:29]
	v_pk_add_f32 v[20:21], v[20:21], v[24:25]
	global_store_dwordx4 v[40:41], v[16:19], off offset:528
	global_store_dwordx4 v[40:41], v[20:23], off offset:512
	s_nop 0
	v_add_co_u32_e32 v16, vcc, s64, v146
	v_lshl_add_u64 v[22:23], v[146:147], 0, s[20:21]
	s_nop 0
	v_addc_co_u32_e32 v17, vcc, 0, v147, vcc
	global_load_dwordx4 v[18:21], v[16:17], off nt
	s_nop 0
	global_load_dwordx4 v[22:25], v[22:23], off offset:16 nt
	s_andn2_b64 vcc, exec, s[2:3]
	s_waitcnt vmcnt(1)
	v_pk_add_f32 v[14:15], v[14:15], v[20:21]
	v_pk_add_f32 v[12:13], v[12:13], v[18:19]
	s_waitcnt vmcnt(0)
	v_pk_add_f32 v[10:11], v[10:11], v[24:25]
	v_pk_add_f32 v[8:9], v[8:9], v[22:23]
	global_store_dwordx4 v[16:17], v[12:15], off
	global_store_dwordx4 v[16:17], v[8:11], off offset:16
	s_nop 1
	v_lshl_add_u64 v[8:9], v[146:147], 0, s[22:23]
	global_load_dwordx4 v[12:15], v[16:17], off offset:512 nt
	s_nop 0
	global_load_dwordx4 v[8:11], v[8:9], off offset:16 nt
	s_waitcnt vmcnt(1)
	v_pk_add_f32 v[6:7], v[6:7], v[14:15]
	v_pk_add_f32 v[4:5], v[4:5], v[12:13]
	s_waitcnt vmcnt(0)
	v_pk_add_f32 v[2:3], v[2:3], v[10:11]
	v_pk_add_f32 v[0:1], v[0:1], v[8:9]
	global_store_dwordx4 v[16:17], v[4:7], off offset:512
	global_store_dwordx4 v[16:17], v[0:3], off offset:528
	s_cbranch_vccnz .LBB0_1228
	s_andn2_b64 vcc, exec, s[6:7]
	s_cbranch_vccnz .LBB0_1227
	s_barrier
	s_branch .LBB0_1227

;     __device__ __forceinline__ void operator()(Acc& acc, const Unit& u, int wr, int wc, int fr, int fq) const {
;         const size_t p0 = u.ooff + (size_t)(wr * 64 + fr) * D + wc * 32 + 8 * fq;
; #pragma unroll
;         for (int ai = 0; ai < 2; ++ai)
; #pragma unroll
;             for (int m = 0; m < 4; ++m)
; #pragma unroll
;                 for (int bj = 0; bj < 2; ++bj) {
;                     const size_t p = p0 + (size_t)(ai * 128 + m * 16) * D + bj * 128;
;                     const f32x4 r0 = *(const f32x4*)(R + p), r1 = *(const f32x4*)(R + p + 4);
;                     *(f32x4*)(O + p) = r0 + acc[ai][bj][m][0] * scale; *(f32x4*)(O + p + 4) = r1 + acc[ai][bj][m][1] * scale;
;                 }
.LBB0_1451:
	v_lshl_add_u64 v[146:147], s[50:51], 2, v[136:137]
	global_load_dwordx4 v[152:155], v[146:147], off offset:16 nt
	global_load_dwordx4 v[156:159], v[146:147], off nt
	s_mov_b32 s33, 0x20000
	s_mov_b64 s[50:51], 0x20000
	s_waitcnt vmcnt(0)
	v_pk_fma_f32 v[122:123], v[122:123], 0.5, v[154:155] op_sel_hi:[1,0,1]
	v_pk_fma_f32 v[126:127], v[126:127], 0.5, v[158:159] op_sel_hi:[1,0,1]
	v_pk_fma_f32 v[124:125], v[124:125], 0.5, v[156:157] op_sel_hi:[1,0,1]
	v_pk_fma_f32 v[120:121], v[120:121], 0.5, v[152:153] op_sel_hi:[1,0,1]
	global_store_dwordx4 v[146:147], v[124:127], off
	global_store_dwordx4 v[146:147], v[120:123], off offset:16
	global_load_dwordx4 v[120:123], v[146:147], off offset:528 nt
	s_nop 0
	global_load_dwordx4 v[124:127], v[146:147], off offset:512 nt
	s_waitcnt vmcnt(1)
	v_pk_fma_f32 v[114:115], v[114:115], 0.5, v[122:123] op_sel_hi:[1,0,1]
	s_waitcnt vmcnt(0)
	v_pk_fma_f32 v[118:119], v[118:119], 0.5, v[126:127] op_sel_hi:[1,0,1]
	v_pk_fma_f32 v[116:117], v[116:117], 0.5, v[124:125] op_sel_hi:[1,0,1]
	v_pk_fma_f32 v[112:113], v[112:113], 0.5, v[120:121] op_sel_hi:[1,0,1]
	v_add_co_u32_e32 v120, vcc, s33, v146
	global_store_dwordx4 v[146:147], v[116:119], off offset:512
	global_store_dwordx4 v[146:147], v[112:115], off offset:528
	v_addc_co_u32_e32 v121, vcc, 0, v147, vcc
	v_lshl_add_u64 v[116:117], v[146:147], 0, s[50:51]
	global_load_dwordx4 v[112:115], v[120:121], off nt
	s_nop 0
	global_load_dwordx4 v[116:119], v[116:117], off offset:16 nt
	s_mov_b64 s[50:51], 0x20200
	s_waitcnt vmcnt(1)
	v_pk_fma_f32 v[110:111], v[110:111], 0.5, v[114:115] op_sel_hi:[1,0,1]
	v_pk_fma_f32 v[108:109], v[108:109], 0.5, v[112:113] op_sel_hi:[1,0,1]
	s_waitcnt vmcnt(0)
	v_pk_fma_f32 v[106:107], v[106:107], 0.5, v[118:119] op_sel_hi:[1,0,1]
	v_pk_fma_f32 v[104:105], v[104:105], 0.5, v[116:117] op_sel_hi:[1,0,1]
	global_store_dwordx4 v[120:121], v[108:111], off
	global_store_dwordx4 v[120:121], v[104:107], off offset:16
	s_nop 0
	v_lshl_add_u64 v[108:109], v[146:147], 0, s[50:51]
	global_load_dwordx4 v[104:107], v[120:121], off offset:512 nt
	s_nop 0
	global_load_dwordx4 v[108:111], v[108:109], off offset:16 nt
	s_mov_b64 s[50:51], 0x160000
	s_waitcnt vmcnt(1)
	v_pk_fma_f32 v[102:103], v[102:103], 0.5, v[106:107] op_sel_hi:[1,0,1]
	v_pk_fma_f32 v[100:101], v[100:101], 0.5, v[104:105] op_sel_hi:[1,0,1]
	s_waitcnt vmcnt(0)
	v_pk_fma_f32 v[98:99], v[98:99], 0.5, v[110:111] op_sel_hi:[1,0,1]
	v_pk_fma_f32 v[96:97], v[96:97], 0.5, v[108:109] op_sel_hi:[1,0,1]
	v_add_co_u32_e32 v104, vcc, s68, v146
	global_store_dwordx4 v[120:121], v[100:103], off offset:512
	global_store_dwordx4 v[120:121], v[96:99], off offset:528
	v_addc_co_u32_e32 v105, vcc, 0, v147, vcc
	v_lshl_add_u64 v[100:101], v[146:147], 0, s[10:11]
	global_load_dwordx4 v[96:99], v[104:105], off nt
	s_nop 0
	global_load_dwordx4 v[100:103], v[100:101], off offset:16 nt
	s_waitcnt vmcnt(1)
	v_pk_fma_f32 v[94:95], v[94:95], 0.5, v[98:99] op_sel_hi:[1,0,1]
	v_pk_fma_f32 v[92:93], v[92:93], 0.5, v[96:97] op_sel_hi:[1,0,1]
	s_waitcnt vmcnt(0)
	v_pk_fma_f32 v[90:91], v[90:91], 0.5, v[102:103] op_sel_hi:[1,0,1]
	v_pk_fma_f32 v[88:89], v[88:89], 0.5, v[100:101] op_sel_hi:[1,0,1]
	global_store_dwordx4 v[104:105], v[92:95], off
	global_store_dwordx4 v[104:105], v[88:91], off offset:16
	s_nop 0
	v_lshl_add_u64 v[92:93], v[146:147], 0, s[12:13]
	global_load_dwordx4 v[88:91], v[104:105], off offset:512 nt
	s_nop 0
	global_load_dwordx4 v[92:95], v[92:93], off offset:16 nt
	s_waitcnt vmcnt(1)
	v_pk_fma_f32 v[86:87], v[86:87], 0.5, v[90:91] op_sel_hi:[1,0,1]
	v_pk_fma_f32 v[84:85], v[84:85], 0.5, v[88:89] op_sel_hi:[1,0,1]
	s_waitcnt vmcnt(0)
	v_pk_fma_f32 v[82:83], v[82:83], 0.5, v[94:95] op_sel_hi:[1,0,1]
	v_pk_fma_f32 v[80:81], v[80:81], 0.5, v[92:93] op_sel_hi:[1,0,1]
	v_add_co_u32_e32 v88, vcc, s69, v146
	global_store_dwordx4 v[104:105], v[84:87], off offset:512
	global_store_dwordx4 v[104:105], v[80:83], off offset:528
	v_addc_co_u32_e32 v89, vcc, 0, v147, vcc
	v_lshl_add_u64 v[84:85], v[146:147], 0, s[14:15]
	global_load_dwordx4 v[80:83], v[88:89], off nt
	s_nop 0
	global_load_dwordx4 v[84:87], v[84:85], off offset:16 nt
	s_waitcnt vmcnt(1)
	v_pk_fma_f32 v[78:79], v[78:79], 0.5, v[82:83] op_sel_hi:[1,0,1]
	v_pk_fma_f32 v[76:77], v[76:77], 0.5, v[80:81] op_sel_hi:[1,0,1]
	s_waitcnt vmcnt(0)
	v_pk_fma_f32 v[74:75], v[74:75], 0.5, v[86:87] op_sel_hi:[1,0,1]
	v_pk_fma_f32 v[72:73], v[72:73], 0.5, v[84:85] op_sel_hi:[1,0,1]
	global_store_dwordx4 v[88:89], v[76:79], off
	global_store_dwordx4 v[88:89], v[72:75], off offset:16
	s_nop 0
	v_lshl_add_u64 v[76:77], v[146:147], 0, s[16:17]
	global_load_dwordx4 v[72:75], v[88:89], off offset:512 nt
	s_nop 0
	global_load_dwordx4 v[76:79], v[76:77], off offset:16 nt
	s_waitcnt vmcnt(1)
	v_pk_fma_f32 v[70:71], v[70:71], 0.5, v[74:75] op_sel_hi:[1,0,1]
	v_pk_fma_f32 v[68:69], v[68:69], 0.5, v[72:73] op_sel_hi:[1,0,1]
	s_waitcnt vmcnt(0)
	v_pk_fma_f32 v[66:67], v[66:67], 0.5, v[78:79] op_sel_hi:[1,0,1]
	v_pk_fma_f32 v[64:65], v[64:65], 0.5, v[76:77] op_sel_hi:[1,0,1]
	v_add_co_u32_e32 v72, vcc, s70, v146
	global_store_dwordx4 v[88:89], v[68:71], off offset:512
	global_store_dwordx4 v[88:89], v[64:67], off offset:528
	v_addc_co_u32_e32 v73, vcc, 0, v147, vcc
	v_lshl_add_u64 v[68:69], v[146:147], 0, s[18:19]
	global_load_dwordx4 v[64:67], v[72:73], off nt
	s_nop 0
	global_load_dwordx4 v[68:71], v[68:69], off offset:16 nt
	s_waitcnt vmcnt(1)
; #define PG8_BAR __builtin_amdgcn_s_barrier()
; template <class Epi, class Sched, bool ALIGN_EPI = true, bool SP2 = true>
; __device__ __forceinline__ void gemm_phase(LAS unsigned char* lds, const bf16_t* Ag, const bf16_t* Btg, const int K, const int lda, const int ldb, const Sched& S, const Epi& E) {
;     ...
;         if (!has_next) break;
; #pragma unroll
;         for (int a = 0; a < 2; ++a)
; #pragma unroll
;             for (int b = 0; b < 2; ++b)
; #pragma unroll
;                 for (int m = 0; m < 4; ++m)
; #pragma unroll
;                     for (int n = 0; n < 2; ++n) acc[a][b][m][n] = (f32x4){0.f, 0.f, 0.f, 0.f};
;         cur = nxt; cA = nA; cB = nB; ++ui;
;         if constexpr (ALIGN_EPI) { if (wr == 1) PG8_BAR; }
;     __device__ __forceinline__ void operator()(Acc& acc, const Unit& u, int wr, int wc, int fr, int fq) const {
;         const size_t p0 = u.ooff + (size_t)(wr * 64 + fr) * D + wc * 32 + 8 * fq;
; #pragma unroll
;         for (int ai = 0; ai < 2; ++ai)
; #pragma unroll
;             for (int m = 0; m < 4; ++m)
; #pragma unroll
;                 for (int bj = 0; bj < 2; ++bj) {
;                     const size_t p = p0 + (size_t)(ai * 128 + m * 16) * D + bj * 128;
;                     const f32x4 r0 = *(const f32x4*)(R + p), r1 = *(const f32x4*)(R + p + 4);
;                     *(f32x4*)(O + p) = r0 + acc[ai][bj][m][0] * scale; *(f32x4*)(O + p + 4) = r1 + acc[ai][bj][m][1] * scale;
;                 }
	v_pk_fma_f32 v[62:63], v[62:63], 0.5, v[66:67] op_sel_hi:[1,0,1]
	v_pk_fma_f32 v[60:61], v[60:61], 0.5, v[64:65] op_sel_hi:[1,0,1]
	s_waitcnt vmcnt(0)
	v_pk_fma_f32 v[58:59], v[58:59], 0.5, v[70:71] op_sel_hi:[1,0,1]
	v_pk_fma_f32 v[56:57], v[56:57], 0.5, v[68:69] op_sel_hi:[1,0,1]
	global_store_dwordx4 v[72:73], v[60:63], off
	global_store_dwordx4 v[72:73], v[56:59], off offset:16
	s_nop 0
	v_lshl_add_u64 v[60:61], v[146:147], 0, s[20:21]
	global_load_dwordx4 v[56:59], v[72:73], off offset:512 nt
	s_nop 0
	global_load_dwordx4 v[60:63], v[60:61], off offset:16 nt
	s_waitcnt vmcnt(1)
	v_pk_fma_f32 v[54:55], v[54:55], 0.5, v[58:59] op_sel_hi:[1,0,1]
	v_pk_fma_f32 v[52:53], v[52:53], 0.5, v[56:57] op_sel_hi:[1,0,1]
	s_waitcnt vmcnt(0)
	v_pk_fma_f32 v[50:51], v[50:51], 0.5, v[62:63] op_sel_hi:[1,0,1]
	v_pk_fma_f32 v[48:49], v[48:49], 0.5, v[60:61] op_sel_hi:[1,0,1]
	v_add_co_u32_e32 v56, vcc, s71, v146
	global_store_dwordx4 v[72:73], v[52:55], off offset:512
	global_store_dwordx4 v[72:73], v[48:51], off offset:528
	v_addc_co_u32_e32 v57, vcc, 0, v147, vcc
	v_lshl_add_u64 v[52:53], v[146:147], 0, s[22:23]
	global_load_dwordx4 v[48:51], v[56:57], off nt
	s_nop 0
	global_load_dwordx4 v[52:55], v[52:53], off offset:16 nt
	s_waitcnt vmcnt(1)
	v_pk_fma_f32 v[46:47], v[46:47], 0.5, v[50:51] op_sel_hi:[1,0,1]
	v_pk_fma_f32 v[44:45], v[44:45], 0.5, v[48:49] op_sel_hi:[1,0,1]
	s_waitcnt vmcnt(0)
	v_pk_fma_f32 v[42:43], v[42:43], 0.5, v[54:55] op_sel_hi:[1,0,1]
	v_pk_fma_f32 v[40:41], v[40:41], 0.5, v[52:53] op_sel_hi:[1,0,1]
	global_store_dwordx4 v[56:57], v[44:47], off
	global_store_dwordx4 v[56:57], v[40:43], off offset:16
	s_nop 0
	v_lshl_add_u64 v[44:45], v[146:147], 0, s[24:25]
	global_load_dwordx4 v[40:43], v[56:57], off offset:512 nt
	s_nop 0
	global_load_dwordx4 v[44:47], v[44:45], off offset:16 nt
	s_waitcnt vmcnt(1)
	v_pk_fma_f32 v[38:39], v[38:39], 0.5, v[42:43] op_sel_hi:[1,0,1]
	v_pk_fma_f32 v[36:37], v[36:37], 0.5, v[40:41] op_sel_hi:[1,0,1]
	s_waitcnt vmcnt(0)
	v_pk_fma_f32 v[34:35], v[34:35], 0.5, v[46:47] op_sel_hi:[1,0,1]
	v_pk_fma_f32 v[32:33], v[32:33], 0.5, v[44:45] op_sel_hi:[1,0,1]
	v_add_co_u32_e32 v40, vcc, s72, v146
	global_store_dwordx4 v[56:57], v[36:39], off offset:512
	global_store_dwordx4 v[56:57], v[32:35], off offset:528
	v_addc_co_u32_e32 v41, vcc, 0, v147, vcc
	v_lshl_add_u64 v[36:37], v[146:147], 0, s[26:27]
	global_load_dwordx4 v[32:35], v[40:41], off nt
	s_nop 0
	global_load_dwordx4 v[36:39], v[36:37], off offset:16 nt
	s_waitcnt vmcnt(1)
	v_pk_fma_f32 v[30:31], v[30:31], 0.5, v[34:35] op_sel_hi:[1,0,1]
	v_pk_fma_f32 v[28:29], v[28:29], 0.5, v[32:33] op_sel_hi:[1,0,1]
	s_waitcnt vmcnt(0)
	v_pk_fma_f32 v[26:27], v[26:27], 0.5, v[38:39] op_sel_hi:[1,0,1]
	v_pk_fma_f32 v[24:25], v[24:25], 0.5, v[36:37] op_sel_hi:[1,0,1]
	global_store_dwordx4 v[40:41], v[28:31], off
	global_store_dwordx4 v[40:41], v[24:27], off offset:16
	s_nop 0
	v_lshl_add_u64 v[28:29], v[146:147], 0, s[28:29]
	global_load_dwordx4 v[24:27], v[40:41], off offset:512 nt
	s_nop 0
	global_load_dwordx4 v[28:31], v[28:29], off offset:16 nt
	s_waitcnt vmcnt(1)
	v_pk_fma_f32 v[22:23], v[22:23], 0.5, v[26:27] op_sel_hi:[1,0,1]
	s_waitcnt vmcnt(0)
	v_pk_fma_f32 v[18:19], v[18:19], 0.5, v[30:31] op_sel_hi:[1,0,1]
	v_pk_fma_f32 v[16:17], v[16:17], 0.5, v[28:29] op_sel_hi:[1,0,1]
	v_pk_fma_f32 v[20:21], v[20:21], 0.5, v[24:25] op_sel_hi:[1,0,1]
	global_store_dwordx4 v[40:41], v[16:19], off offset:528
	global_store_dwordx4 v[40:41], v[20:23], off offset:512
	s_nop 0
	v_add_co_u32_e32 v16, vcc, s73, v146
	v_lshl_add_u64 v[22:23], v[146:147], 0, s[50:51]
	s_nop 0
	v_addc_co_u32_e32 v17, vcc, 0, v147, vcc
	global_load_dwordx4 v[18:21], v[16:17], off nt
	s_nop 0
	global_load_dwordx4 v[22:25], v[22:23], off offset:16 nt
	s_mov_b64 s[50:51], -1
	s_andn2_b64 vcc, exec, s[2:3]
	s_waitcnt vmcnt(1)
	v_pk_fma_f32 v[14:15], v[14:15], 0.5, v[20:21] op_sel_hi:[1,0,1]
	v_pk_fma_f32 v[12:13], v[12:13], 0.5, v[18:19] op_sel_hi:[1,0,1]
	s_waitcnt vmcnt(0)
	v_pk_fma_f32 v[10:11], v[10:11], 0.5, v[24:25] op_sel_hi:[1,0,1]
	v_pk_fma_f32 v[8:9], v[8:9], 0.5, v[22:23] op_sel_hi:[1,0,1]
	global_store_dwordx4 v[16:17], v[12:15], off
	global_store_dwordx4 v[16:17], v[8:11], off offset:16
	s_nop 1
	v_lshl_add_u64 v[8:9], v[146:147], 0, s[30:31]
	global_load_dwordx4 v[12:15], v[16:17], off offset:512 nt
	s_nop 0
	global_load_dwordx4 v[8:11], v[8:9], off offset:16 nt
	s_waitcnt vmcnt(1)
	v_pk_fma_f32 v[6:7], v[6:7], 0.5, v[14:15] op_sel_hi:[1,0,1]
	v_pk_fma_f32 v[4:5], v[4:5], 0.5, v[12:13] op_sel_hi:[1,0,1]
	s_waitcnt vmcnt(0)
	v_pk_fma_f32 v[2:3], v[2:3], 0.5, v[10:11] op_sel_hi:[1,0,1]
	v_pk_fma_f32 v[0:1], v[0:1], 0.5, v[8:9] op_sel_hi:[1,0,1]
	global_store_dwordx4 v[16:17], v[4:7], off offset:512
	global_store_dwordx4 v[16:17], v[0:3], off offset:528
	s_cbranch_vccnz .LBB0_1440
	s_andn2_b64 vcc, exec, s[4:5]
	s_cbranch_vccnz .LBB0_1439
	s_barrier
	s_branch .LBB0_1439
